# packed f32 ops of P1 split into scalar pairs (on top of the best version)
# speedup vs baseline: 1.0001x; 1.0001x over previous
; __global__ void __launch_bounds__(NTHR, 2) mega(Args args) {
;     ...
;         for (int mi = mi0; mi < mcnt; mi += 4 * mstep) {
;             f32x4 v[4][4]; float ss[4]; int mrow_[4]; bool ok[4];
; #pragma unroll
;             for (int q = 0; q < 4; ++q) {
;                 const int mq = mi + q * mstep; ok[q] = mq < mcnt; const int mqq = ok[q] ? mq : mi;
;                 const int m = ctxwg ? cb_ * LT + mqq : (nlat > 0 ? (mqq >> 11) * LT + CT + (mqq & 2047) : mqq);
;                 mrow_[q] = m;
;                 const int b = m / LT, w = m % LT;
;                 const float* src = w < CT ? ctx + ((size_t)b * CT + w) * D : x + ((size_t)b * L + (w - CT)) * D;
;                 ss[q] = 0.f;
; #pragma unroll
;                 for (int j2 = 0; j2 < 4; ++j2) { v[q][j2] = ((const f32x4*)src)[lane + 64 * j2]; }
;             }
; #pragma unroll
;             for (int q = 0; q < 4; ++q) {
; #pragma unroll
;                 for (int j2 = 0; j2 < 4; ++j2) ss[q] += (v[q][j2].x * v[q][j2].x + v[q][j2].y * v[q][j2].y) + (v[q][j2].z * v[q][j2].z + v[q][j2].w * v[q][j2].w);
;                 ss[q] = wave_sum(ss[q]);
.LBB0_132:
	s_mul_hi_i32 s5, s4, 0x38e38e39
	s_lshr_b32 s6, s5, 31
	s_ashr_i32 s5, s5, 9
	s_add_i32 s80, s5, s6
	s_mul_i32 s5, s80, 0xfffff700
	s_add_i32 s5, s4, s5
	s_cmpk_lt_i32 s5, 0x100
	s_cselect_b64 s[82:83], -1, 0
	s_ashr_i32 s81, s80, 31
	s_add_i32 s8, s5, 0xffffff00
	s_ashr_i32 s9, s5, 31
	s_and_b64 s[6:7], s[82:83], exec
	s_cselect_b32 s6, s5, s8
	s_cselect_b32 s5, 20, 23
	s_cselect_b32 s14, s41, s37
	s_cselect_b32 s15, s40, s36
	s_cselect_b32 s7, s9, 0
	s_lshl_b64 s[8:9], s[80:81], s5
	s_add_u32 s5, s15, s8
	s_addc_u32 s8, s14, s9
	s_lshl_b64 s[6:7], s[6:7], 12
	s_add_u32 s6, s5, s6
	s_addc_u32 s7, s8, s7
	global_load_dwordx4 v[2:5], v75, s[6:7]
	global_load_dwordx4 v[58:61], v75, s[6:7] offset:1024
	global_load_dwordx4 v[38:41], v75, s[6:7] offset:2048
	s_waitcnt lgkmcnt(0)
	global_load_dwordx4 v[26:29], v75, s[6:7] offset:3072
	s_add_i32 s52, s33, s4
	s_cmpk_lt_i32 s52, 0x4800
	s_cselect_b32 s5, s52, s4
	s_mul_hi_i32 s6, s5, 0x38e38e39
	s_lshr_b32 s7, s6, 31
	s_ashr_i32 s6, s6, 9
	s_add_i32 s64, s6, s7
	s_mul_i32 s6, s64, 0x900
	s_sub_i32 s5, s5, s6
	s_cmpk_lt_i32 s5, 0x100
	s_cselect_b64 s[70:71], -1, 0
	s_ashr_i32 s65, s64, 31
	s_ashr_i32 s8, s5, 31
	s_add_i32 s9, s5, 0xffffff00
	s_and_b64 s[6:7], s[70:71], exec
	s_cselect_b32 s6, s5, s9
	s_cselect_b32 s5, 20, 23
	s_cselect_b32 s14, s41, s37
	s_cselect_b32 s15, s40, s36
	s_cselect_b32 s7, s8, 0
	s_lshl_b64 s[8:9], s[64:65], s5
	s_add_u32 s5, s15, s8
	s_addc_u32 s8, s14, s9
	s_lshl_b64 s[6:7], s[6:7], 12
	s_add_u32 s84, s5, s6
	s_addc_u32 s85, s8, s7
	s_add_i32 s20, s10, s4
	s_cmpk_lt_i32 s20, 0x4800
	s_cselect_b64 s[46:47], -1, 0
	s_and_b64 s[6:7], s[46:47], exec
	s_cselect_b32 s5, s20, s4
	s_mul_hi_i32 s6, s5, 0x38e38e39
	s_lshr_b32 s7, s6, 31
	s_ashr_i32 s6, s6, 9
	s_add_i32 s38, s6, s7
	s_mul_i32 s6, s38, 0x900
	s_sub_i32 s5, s5, s6
	s_cmpk_lt_i32 s5, 0x100
	s_cselect_b64 s[48:49], -1, 0
	s_ashr_i32 s39, s38, 31
	s_ashr_i32 s8, s5, 31
	s_add_i32 s9, s5, 0xffffff00
	s_and_b64 s[6:7], s[48:49], exec
	s_cselect_b32 s6, s5, s9
	s_cselect_b32 s5, 20, 23
	s_cselect_b32 s14, s41, s37
	s_cselect_b32 s15, s40, s36
	s_cselect_b32 s7, s8, 0
	s_lshl_b64 s[8:9], s[38:39], s5
	s_add_u32 s5, s15, s8
	s_addc_u32 s8, s14, s9
	s_lshl_b64 s[6:7], s[6:7], 12
	s_add_u32 s86, s5, s6
	s_addc_u32 s87, s8, s7
	s_add_i32 s6, s11, s4
	s_cmpk_lt_i32 s6, 0x4800
	s_cselect_b64 s[14:15], -1, 0
	s_and_b64 s[8:9], s[14:15], exec
	s_cselect_b32 s5, s6, s4
	s_mul_hi_i32 s7, s5, 0x38e38e39
	s_lshr_b32 s8, s7, 31
	s_ashr_i32 s7, s7, 9
	s_add_i32 s8, s7, s8
	s_mul_i32 s7, s8, 0x900
	s_sub_i32 s5, s5, s7
	s_cmpk_lt_i32 s5, 0x100
	s_cselect_b64 s[16:17], -1, 0
	s_ashr_i32 s9, s8, 31
	s_ashr_i32 s7, s5, 31
	s_add_i32 s21, s5, 0xffffff00
	s_and_b64 s[42:43], s[16:17], exec
	s_cselect_b32 s42, s5, s21
	s_cselect_b32 s5, 20, 23
	s_cselect_b32 s39, s41, s37
	s_cselect_b32 s53, s40, s36
	s_cselect_b32 s43, s7, 0
	s_lshl_b64 s[68:69], s[8:9], s5
	s_add_u32 s5, s53, s68
	s_addc_u32 s7, s39, s69
	s_lshl_b64 s[42:43], s[42:43], 12
	s_add_u32 s88, s5, s42
	s_addc_u32 s89, s7, s43
	s_and_b64 s[42:43], s[82:83], exec
	s_cselect_b32 s5, 8, s80
	s_mul_hi_i32 s7, s5, 0x6000
	s_mulk_i32 s5, 0x6000
	s_add_u32 s80, s28, s5
	s_addc_u32 s81, s29, s7
	s_add_u32 s82, s80, 0x1000
	s_addc_u32 s83, s81, 0
	global_load_dwordx4 v[6:9], v[62:63], off
	s_waitcnt vmcnt(4)
	v_mul_f32_e32 v14, v4, v4
	v_mul_f32_e32 v15, v5, v5
	v_mul_f32_e32 v18, v2, v2
	v_mul_f32_e32 v19, v3, v3
	global_load_dwordx4 v[10:13], v77, s[82:83]
	v_pk_mov_b32 v[20:21], v[18:19], v[14:15] op_sel:[1,0]
	v_mov_b32_e32 v19, v15
	global_load_dwordx4 v[14:17], v77, s[80:81]
	v_add_f32_e32 v18, v20, v18
	v_add_f32_e32 v19, v21, v19
	s_waitcnt vmcnt(5)
	v_mul_f32_e32 v20, v60, v60
	v_mul_f32_e32 v21, v61, v61
	v_mul_f32_e32 v22, v58, v58
	v_mul_f32_e32 v23, v59, v59
	v_pk_add_f32 v[18:19], v[18:19], v[18:19] op_sel:[0,1] op_sel_hi:[1,0]
	v_pk_mov_b32 v[24:25], v[22:23], v[20:21] op_sel:[1,0]
	v_mov_b32_e32 v23, v21
	v_add_f32_e32 v20, v24, v22
	v_add_f32_e32 v21, v25, v23
	s_waitcnt vmcnt(3)
	v_mul_f32_e32 v22, v26, v26
	v_mul_f32_e32 v23, v27, v27
	v_pk_add_f32 v[20:21], v[20:21], v[20:21] op_sel:[0,1] op_sel_hi:[1,0]
	v_mov_b32_e32 v19, v22
	v_mov_b32_e32 v21, v23
	v_add_f32_e32 v18, v18, v20
	v_add_f32_e32 v19, v19, v21
	v_mul_f32_e32 v20, v39, v39
	v_mul_f32_e32 v22, v41, v41
	v_mul_f32_e32 v24, v28, v28
	v_mul_f32_e32 v25, v29, v29
	v_fma_f32 v21, v39, v39, v20
	v_fma_f32 v20, v38, v38, v20
	v_fma_f32 v23, v41, v41, v22
	v_fma_f32 v22, v40, v40, v22
	v_mov_b32_e32 v21, v24
	v_mov_b32_e32 v23, v25
	v_add_f32_e32 v20, v20, v22
	v_add_f32_e32 v21, v21, v23
	s_ashr_i32 s5, s4, 31
	v_add_f32_e32 v18, v18, v20
	v_add_f32_e32 v19, v19, v21
	s_lshl_b64 s[42:43], s[4:5], 11
	v_add_f32_e32 v18, v18, v19
	ds_bpermute_b32 v19, v1, v18
	v_lshl_add_u64 v[68:69], v[64:65], 0, s[42:43]
	global_load_dwordx4 v[54:57], v75, s[84:85]
	global_load_dwordx4 v[50:53], v75, s[84:85] offset:1024
	global_load_dwordx4 v[46:49], v75, s[84:85] offset:2048
	global_load_dwordx4 v[42:45], v75, s[84:85] offset:3072
	global_load_dwordx4 v[34:37], v75, s[86:87]
	global_load_dwordx4 v[30:33], v75, s[86:87] offset:1024
	s_cmpk_gt_i32 s52, 0x47ff
	s_waitcnt lgkmcnt(0)
	v_add_f32_e32 v18, v18, v19
	ds_bpermute_b32 v19, v70, v18
	s_waitcnt lgkmcnt(0)
	v_add_f32_e32 v18, v18, v19
	ds_bpermute_b32 v19, v71, v18
	s_waitcnt lgkmcnt(0)
	v_add_f32_e32 v18, v18, v19
	ds_bpermute_b32 v19, v72, v18
	s_waitcnt lgkmcnt(0)
	v_add_f32_e32 v18, v18, v19
	ds_bpermute_b32 v19, v73, v18
	s_waitcnt lgkmcnt(0)
	v_add_f32_e32 v18, v18, v19
	ds_bpermute_b32 v19, v74, v18
	s_waitcnt lgkmcnt(0)
; __device__ __forceinline__ unsigned pk2(float lo, float hi) { return f2bf(lo) | (f2bf(hi) << 16); }
; __global__ void __launch_bounds__(NTHR, 2) mega(Args args) {
;     ...
;                 ss[q] = wave_sum(ss[q]);
;             }
; #pragma unroll
;             for (int q = 0; q < 4; ++q) {
;                 if (!ok[q]) continue;
;                 const int m = mrow_[q]; const int b = m / LT, w = m % LT;
;                 const float* mrow = mod + (size_t)(w < CT ? 8 : b) * NMODC;
;                 const float rstd = rsqrtf(ss[q] * (1.f / D) + EPS);
; #pragma unroll
;                 for (int j2 = 0; j2 < 4; ++j2) { const int k0 = 4 * lane + 256 * j2;
;                     const f32x4 g = *(const f32x4*)(g1 + k0), sc = *(const f32x4*)(mrow + D + k0), sh = *(const f32x4*)(mrow + k0);
;                     const f32x4 y = v[q][j2] * rstd * g; const f32x4 h = y * (sc + 1.f) + sh;
;                     v2u pk; pk.x = pk2(h.x, h.y); pk.y = pk2(h.z, h.w);
;                     *(v2u*)(HB + (size_t)m * D + k0) = pk; }
	v_add_f32_e32 v18, v18, v19
	v_fmamk_f32 v18, v18, 0x3a800000, v76
	v_mul_f32_e32 v19, 0x4b800000, v18
	v_cmp_gt_f32_e32 vcc, s19, v18
	s_waitcnt vmcnt(3)
	v_mul_f32_e32 v94, v49, v49
	v_cndmask_b32_e32 v18, v18, v19, vcc
	v_rsq_f32_e32 v18, v18
	s_waitcnt vmcnt(2)
	v_mul_f32_e32 v95, v43, v43
	v_mul_f32_e32 v96, v45, v45
	v_fmac_f32_e32 v94, v48, v48
	v_mul_f32_e32 v19, 0x45800000, v18
	v_cndmask_b32_e32 v66, v18, v19, vcc
	v_mul_f32_e32 v4, v66, v4
	v_mul_f32_e32 v5, v66, v5
	v_mul_f32_e32 v2, v66, v2
	v_mul_f32_e32 v3, v66, v3
	v_mul_f32_e32 v2, v6, v2
	v_mul_f32_e32 v3, v7, v3
	v_mul_f32_e32 v4, v8, v4
	v_mul_f32_e32 v5, v9, v5
	v_add_f32_e32 v8, 1.0, v10
	v_add_f32_e32 v9, 1.0, v11
	v_add_f32_e32 v6, 1.0, v12
	v_add_f32_e32 v7, 1.0, v13
	v_fma_f32 v2, v8, v2, v14
	v_fma_f32 v3, v9, v3, v15
	v_fma_f32 v4, v6, v4, v16
	v_fma_f32 v5, v7, v5, v17
	v_bfe_u32 v6, v2, 16, 1
	v_add3_u32 v2, v2, v6, s34
	v_bfe_u32 v6, v3, 16, 1
	v_lshrrev_b32_e32 v2, 16, v2
	v_add3_u32 v3, v3, v6, s34
	v_and_or_b32 v82, v3, s35, v2
	v_bfe_u32 v2, v4, 16, 1
	v_add3_u32 v2, v4, v2, s34
	v_bfe_u32 v3, v5, 16, 1
	v_lshrrev_b32_e32 v2, 16, v2
	v_add3_u32 v3, v5, v3, s34
	v_and_or_b32 v83, v3, s35, v2
	global_load_dwordx4 v[22:25], v75, s[86:87] offset:2048
	global_load_dwordx4 v[18:21], v75, s[86:87] offset:3072
	global_load_dwordx4 v[14:17], v75, s[88:89]
	global_load_dwordx4 v[10:13], v75, s[88:89] offset:1024
	global_load_dwordx4 v[6:9], v75, s[88:89] offset:2048
	global_load_dwordx4 v[2:5], v75, s[88:89] offset:3072
	v_mul_f32_e32 v60, v66, v60
	v_mul_f32_e32 v61, v66, v61
	global_store_dwordx2 v[68:69], v[82:83], off
	global_load_dwordx4 v[82:85], v[62:63], off offset:1024
	s_nop 0
	global_load_dwordx4 v[86:89], v78, s[82:83]
	global_load_dwordx4 v[90:93], v77, s[80:81] offset:1024
	v_mul_f32_e32 v58, v66, v58
	v_mul_f32_e32 v59, v66, v59
	v_mul_f32_e32 v40, v66, v40
	v_mul_f32_e32 v41, v66, v41
	v_mul_f32_e32 v38, v66, v38
	v_mul_f32_e32 v39, v66, v39
	v_fmac_f32_e32 v95, v42, v42
	v_fmac_f32_e32 v96, v44, v44
	s_waitcnt vmcnt(2)
	v_mul_f32_e32 v58, v82, v58
	v_mul_f32_e32 v59, v83, v59
	v_mul_f32_e32 v60, v84, v60
	v_mul_f32_e32 v61, v85, v61
	s_waitcnt vmcnt(1)
	v_add_f32_e32 v82, 1.0, v88
	v_add_f32_e32 v83, 1.0, v89
	v_add_f32_e32 v84, 1.0, v86
	v_add_f32_e32 v85, 1.0, v87
	s_waitcnt vmcnt(0)
	v_fma_f32 v60, v82, v60, v92
	v_fma_f32 v61, v83, v61, v93
	v_fma_f32 v58, v84, v58, v90
	v_fma_f32 v59, v85, v59, v91
	v_bfe_u32 v83, v60, 16, 1
	v_bfe_u32 v81, v58, 16, 1
	v_bfe_u32 v82, v59, 16, 1
	v_bfe_u32 v84, v61, 16, 1
	v_add3_u32 v58, v58, v81, s34
	v_add3_u32 v60, v60, v83, s34
	v_add3_u32 v59, v59, v82, s34
	v_add3_u32 v61, v61, v84, s34
	v_lshrrev_b32_e32 v58, 16, v58
	v_lshrrev_b32_e32 v60, 16, v60
	v_and_or_b32 v58, v59, s35, v58
	v_and_or_b32 v59, v61, s35, v60
	global_store_dwordx2 v[68:69], v[58:59], off offset:512
	global_load_dwordx4 v[58:61], v[62:63], off offset:2048
	s_nop 0
	global_load_dwordx4 v[82:85], v79, s[82:83]
	global_load_dwordx4 v[86:89], v77, s[80:81] offset:2048
	v_mul_f32_e32 v81, v55, v55
	v_mul_f32_e32 v90, v57, v57
	v_mul_f32_e32 v91, v51, v51
	v_mul_f32_e32 v92, v53, v53
	v_mul_f32_e32 v93, v47, v47
	v_fmac_f32_e32 v81, v54, v54
	v_fmac_f32_e32 v90, v56, v56
	v_fmac_f32_e32 v91, v50, v50
	v_fmac_f32_e32 v92, v52, v52
	v_fmac_f32_e32 v93, v46, v46
	v_add_f32_e32 v81, v81, v90
	v_add_f32_e32 v90, v91, v92
	v_add_f32_e32 v91, v93, v94
	v_add_f32_e32 v81, v81, v90
	v_add_f32_e32 v92, v95, v96
	v_add_f32_e32 v81, v81, v91
	v_mul_f32_e32 v91, v35, v35
	v_add_f32_e32 v81, v81, v92
	v_mul_f32_e32 v92, v25, v25
	v_fmac_f32_e32 v91, v34, v34
	v_mul_f32_e32 v93, v19, v19
	v_mul_f32_e32 v94, v21, v21
	v_fmac_f32_e32 v92, v24, v24
	v_fmac_f32_e32 v93, v18, v18
	v_fmac_f32_e32 v94, v20, v20
	ds_bpermute_b32 v90, v1, v81
	v_mul_f32_e32 v95, v3, v3
	v_mul_f32_e32 v96, v5, v5
	v_fmac_f32_e32 v95, v2, v2
	v_fmac_f32_e32 v96, v4, v4
	s_waitcnt lgkmcnt(0)
	v_add_f32_e32 v81, v81, v90
	ds_bpermute_b32 v90, v70, v81
	s_waitcnt lgkmcnt(0)
	v_add_f32_e32 v81, v81, v90
	ds_bpermute_b32 v90, v71, v81
	s_waitcnt lgkmcnt(0)
	v_add_f32_e32 v81, v81, v90
	ds_bpermute_b32 v90, v72, v81
	s_waitcnt lgkmcnt(0)
	v_add_f32_e32 v81, v81, v90
	ds_bpermute_b32 v90, v73, v81
	s_waitcnt vmcnt(2)
	v_mul_f32_e32 v38, v58, v38
	v_mul_f32_e32 v39, v59, v39
	v_mul_f32_e32 v40, v60, v40
	v_mul_f32_e32 v41, v61, v41
	s_waitcnt vmcnt(1)
	v_add_f32_e32 v58, 1.0, v84
	v_add_f32_e32 v59, 1.0, v85
	v_add_f32_e32 v60, 1.0, v82
	v_add_f32_e32 v61, 1.0, v83
	s_waitcnt vmcnt(0)
	v_fma_f32 v40, v58, v40, v88
	v_fma_f32 v41, v59, v41, v89
	v_fma_f32 v38, v60, v38, v86
	v_fma_f32 v39, v61, v39, v87
	v_bfe_u32 v60, v40, 16, 1
	v_bfe_u32 v58, v38, 16, 1
	v_bfe_u32 v59, v39, 16, 1
	v_bfe_u32 v61, v41, 16, 1
	v_add3_u32 v38, v38, v58, s34
	v_add3_u32 v40, v40, v60, s34
	v_add3_u32 v39, v39, v59, s34
	v_add3_u32 v41, v41, v61, s34
	v_lshrrev_b32_e32 v38, 16, v38
	v_lshrrev_b32_e32 v40, 16, v40
	v_and_or_b32 v38, v39, s35, v38
	v_and_or_b32 v39, v41, s35, v40
	global_store_dwordx2 v[68:69], v[38:39], off offset:1024
	global_load_dwordx4 v[58:61], v[62:63], off offset:3072
	global_load_dwordx4 v[82:85], v80, s[82:83]
	global_load_dwordx4 v[86:89], v77, s[80:81] offset:3072
	v_mul_f32_e32 v38, v37, v37
	v_mul_f32_e32 v39, v31, v31
	v_mul_f32_e32 v40, v33, v33
	v_mul_f32_e32 v41, v23, v23
	v_fmac_f32_e32 v38, v36, v36
	v_fmac_f32_e32 v39, v30, v30
	v_fmac_f32_e32 v40, v32, v32
	v_fmac_f32_e32 v41, v22, v22
	v_add_f32_e32 v38, v91, v38
	v_add_f32_e32 v39, v39, v40
	v_add_f32_e32 v40, v41, v92
	v_add_f32_e32 v38, v38, v39
	v_add_f32_e32 v41, v93, v94
	v_add_f32_e32 v38, v38, v40
	v_add_f32_e32 v38, v38, v41
	v_mul_f32_e32 v40, v15, v15
	v_mul_f32_e32 v41, v17, v17
	v_mul_f32_e32 v91, v11, v11
	v_mul_f32_e32 v92, v13, v13
	v_mul_f32_e32 v93, v7, v7
	v_mul_f32_e32 v94, v9, v9
	v_fmac_f32_e32 v40, v14, v14
	v_fmac_f32_e32 v41, v16, v16
	v_fmac_f32_e32 v91, v10, v10
	v_fmac_f32_e32 v92, v12, v12
	v_fmac_f32_e32 v93, v6, v6
	v_fmac_f32_e32 v94, v8, v8
	v_add_f32_e32 v40, v40, v41
	v_add_f32_e32 v41, v91, v92
	v_add_f32_e32 v91, v93, v94
	v_add_f32_e32 v40, v40, v41
	v_add_f32_e32 v92, v95, v96
	v_add_f32_e32 v40, v40, v91
	v_add_f32_e32 v40, v40, v92
	ds_bpermute_b32 v39, v1, v38
	ds_bpermute_b32 v41, v1, v40
	s_waitcnt lgkmcnt(1)
; __device__ __forceinline__ unsigned pk2(float lo, float hi) { return f2bf(lo) | (f2bf(hi) << 16); }
; __global__ void __launch_bounds__(NTHR, 2) mega(Args args) {
;     ...
; #pragma unroll
;             for (int q = 0; q < 4; ++q) {
;                 if (!ok[q]) continue;
;                 const int m = mrow_[q]; const int b = m / LT, w = m % LT;
;                 const float* mrow = mod + (size_t)(w < CT ? 8 : b) * NMODC;
;                 const float rstd = rsqrtf(ss[q] * (1.f / D) + EPS);
; #pragma unroll
;                 for (int j2 = 0; j2 < 4; ++j2) { const int k0 = 4 * lane + 256 * j2;
;                     const f32x4 g = *(const f32x4*)(g1 + k0), sc = *(const f32x4*)(mrow + D + k0), sh = *(const f32x4*)(mrow + k0);
;                     const f32x4 y = v[q][j2] * rstd * g; const f32x4 h = y * (sc + 1.f) + sh;
;                     v2u pk; pk.x = pk2(h.x, h.y); pk.y = pk2(h.z, h.w);
;                     *(v2u*)(HB + (size_t)m * D + k0) = pk; }
	v_add_f32_e32 v38, v38, v39
	s_waitcnt lgkmcnt(0)
	v_add_f32_e32 v40, v40, v41
	ds_bpermute_b32 v39, v70, v38
	ds_bpermute_b32 v41, v70, v40
	s_waitcnt lgkmcnt(1)
	v_add_f32_e32 v38, v38, v39
	s_waitcnt lgkmcnt(0)
	v_add_f32_e32 v40, v40, v41
	ds_bpermute_b32 v39, v71, v38
	ds_bpermute_b32 v41, v71, v40
	s_waitcnt lgkmcnt(1)
	v_add_f32_e32 v91, v38, v39
	s_waitcnt lgkmcnt(0)
	v_add_f32_e32 v40, v40, v41
	ds_bpermute_b32 v92, v72, v91
	ds_bpermute_b32 v41, v72, v40
	v_add_f32_e32 v38, v81, v90
	ds_bpermute_b32 v39, v74, v38
	s_waitcnt lgkmcnt(2)
	v_add_f32_e32 v81, v91, v92
	s_waitcnt lgkmcnt(1)
	v_add_f32_e32 v93, v40, v41
	ds_bpermute_b32 v92, v73, v81
	ds_bpermute_b32 v94, v73, v93
	v_mul_f32_e32 v40, v66, v28
	v_mul_f32_e32 v41, v66, v29
	v_mul_f32_e32 v90, v66, v26
	v_mul_f32_e32 v91, v66, v27
	s_waitcnt lgkmcnt(1)
	v_add_f32_e32 v28, v81, v92
	s_waitcnt lgkmcnt(0)
	v_add_f32_e32 v26, v93, v94
	ds_bpermute_b32 v29, v74, v28
	ds_bpermute_b32 v27, v74, v26
	s_waitcnt vmcnt(2)
	v_mul_f32_e32 v58, v58, v90
	v_mul_f32_e32 v59, v59, v91
	v_mul_f32_e32 v40, v60, v40
	v_mul_f32_e32 v41, v61, v41
	s_waitcnt vmcnt(1)
	v_add_f32_e32 v60, 1.0, v84
	v_add_f32_e32 v61, 1.0, v85
	v_add_f32_e32 v82, 1.0, v82
	v_add_f32_e32 v83, 1.0, v83
	s_waitcnt vmcnt(0)
	v_fma_f32 v40, v60, v40, v88
	v_fma_f32 v41, v61, v41, v89
	v_fma_f32 v58, v82, v58, v86
	v_fma_f32 v59, v83, v59, v87
	v_bfe_u32 v66, v40, 16, 1
	v_bfe_u32 v60, v58, 16, 1
	v_bfe_u32 v61, v59, 16, 1
	v_bfe_u32 v81, v41, 16, 1
	v_add3_u32 v58, v58, v60, s34
	v_add3_u32 v40, v40, v66, s34
	v_add3_u32 v59, v59, v61, s34
	v_add3_u32 v41, v41, v81, s34
	v_lshrrev_b32_e32 v58, 16, v58
	v_lshrrev_b32_e32 v60, 16, v40
	v_and_or_b32 v40, v59, s35, v58
	v_and_or_b32 v41, v41, s35, v60
	global_store_dwordx2 v[68:69], v[40:41], off offset:1536
	s_cbranch_scc1 .LBB0_135
	s_and_b64 s[42:43], s[70:71], exec
	s_cselect_b32 s5, 8, s64
	s_mul_hi_i32 s7, s5, 0x6000
	s_mulk_i32 s5, 0x6000
	s_add_u32 s64, s28, s5
	s_addc_u32 s65, s29, s7
	s_add_u32 s70, s64, 0x1000
	global_load_dwordx4 v[58:61], v[62:63], off
	s_addc_u32 s71, s65, 0
	global_load_dwordx4 v[82:85], v77, s[70:71]
	global_load_dwordx4 v[86:89], v77, s[64:65]
	v_add_f32_e32 v38, v38, v39
	v_fmamk_f32 v38, v38, 0x3a800000, v76
	v_mul_f32_e32 v39, 0x4b800000, v38
	v_cmp_gt_f32_e32 vcc, s19, v38
	s_ashr_i32 s53, s52, 31
	s_lshl_b64 s[42:43], s[52:53], 11
	v_cndmask_b32_e32 v38, v38, v39, vcc
	v_rsq_f32_e32 v38, v38
	v_lshl_add_u64 v[68:69], v[64:65], 0, s[42:43]
	v_mul_f32_e32 v39, 0x45800000, v38
	v_cndmask_b32_e32 v66, v38, v39, vcc
	v_mul_f32_e32 v38, v66, v56
	v_mul_f32_e32 v39, v66, v57
	v_mul_f32_e32 v40, v66, v54
	v_mul_f32_e32 v41, v66, v55
	v_mul_f32_e32 v52, v66, v52
	v_mul_f32_e32 v53, v66, v53
	v_mul_f32_e32 v50, v66, v50
	v_mul_f32_e32 v51, v66, v51
	v_mul_f32_e32 v48, v66, v48
	v_mul_f32_e32 v49, v66, v49
	v_mul_f32_e32 v46, v66, v46
	v_mul_f32_e32 v47, v66, v47
	v_mul_f32_e32 v44, v66, v44
	v_mul_f32_e32 v45, v66, v45
	v_mul_f32_e32 v42, v66, v42
	v_mul_f32_e32 v43, v66, v43
	s_waitcnt vmcnt(2)
	v_mul_f32_e32 v40, v58, v40
	v_mul_f32_e32 v41, v59, v41
	v_mul_f32_e32 v38, v60, v38
	v_mul_f32_e32 v39, v61, v39
	s_waitcnt vmcnt(1)
	v_add_f32_e32 v54, 1.0, v84
	v_add_f32_e32 v55, 1.0, v85
	v_add_f32_e32 v56, 1.0, v82
	v_add_f32_e32 v57, 1.0, v83
	s_waitcnt vmcnt(0)
	v_fma_f32 v38, v54, v38, v88
	v_fma_f32 v39, v55, v39, v89
	v_fma_f32 v40, v56, v40, v86
	v_fma_f32 v41, v57, v41, v87
	v_bfe_u32 v56, v38, 16, 1
	v_bfe_u32 v54, v40, 16, 1
	v_bfe_u32 v55, v41, 16, 1
	v_bfe_u32 v57, v39, 16, 1
	v_add3_u32 v40, v40, v54, s34
	v_add3_u32 v38, v38, v56, s34
	v_add3_u32 v41, v41, v55, s34
	v_add3_u32 v39, v39, v57, s34
	v_lshrrev_b32_e32 v40, 16, v40
	v_lshrrev_b32_e32 v54, 16, v38
	v_and_or_b32 v38, v41, s35, v40
	v_and_or_b32 v39, v39, s35, v54
	global_store_dwordx2 v[68:69], v[38:39], off
	global_load_dwordx4 v[38:41], v[62:63], off offset:1024
	s_nop 0
	global_load_dwordx4 v[54:57], v78, s[70:71]
	global_load_dwordx4 v[58:61], v77, s[64:65] offset:1024
	s_waitcnt vmcnt(2)
	v_mul_f32_e32 v38, v38, v50
	v_mul_f32_e32 v39, v39, v51
	v_mul_f32_e32 v40, v40, v52
	v_mul_f32_e32 v41, v41, v53
	s_waitcnt vmcnt(1)
	v_add_f32_e32 v50, 1.0, v56
	v_add_f32_e32 v51, 1.0, v57
	v_add_f32_e32 v52, 1.0, v54
	v_add_f32_e32 v53, 1.0, v55
	s_waitcnt vmcnt(0)
	v_fma_f32 v40, v50, v40, v60
	v_fma_f32 v41, v51, v41, v61
	v_fma_f32 v38, v52, v38, v58
	v_fma_f32 v39, v53, v39, v59
	v_bfe_u32 v52, v40, 16, 1
	v_bfe_u32 v50, v38, 16, 1
	v_bfe_u32 v51, v39, 16, 1
	v_bfe_u32 v53, v41, 16, 1
	v_add3_u32 v38, v38, v50, s34
	v_add3_u32 v40, v40, v52, s34
	v_add3_u32 v39, v39, v51, s34
	v_add3_u32 v41, v41, v53, s34
	v_lshrrev_b32_e32 v38, 16, v38
	v_lshrrev_b32_e32 v40, 16, v40
	v_and_or_b32 v38, v39, s35, v38
	v_and_or_b32 v39, v41, s35, v40
	global_store_dwordx2 v[68:69], v[38:39], off offset:512
	global_load_dwordx4 v[38:41], v[62:63], off offset:2048
	s_nop 0
	global_load_dwordx4 v[50:53], v79, s[70:71]
	global_load_dwordx4 v[54:57], v77, s[64:65] offset:2048
	s_waitcnt vmcnt(2)
	v_mul_f32_e32 v38, v38, v46
	v_mul_f32_e32 v39, v39, v47
	v_mul_f32_e32 v40, v40, v48
	v_mul_f32_e32 v41, v41, v49
	s_waitcnt vmcnt(1)
	v_add_f32_e32 v46, 1.0, v52
	v_add_f32_e32 v47, 1.0, v53
	v_add_f32_e32 v48, 1.0, v50
	v_add_f32_e32 v49, 1.0, v51
	s_waitcnt vmcnt(0)
	v_fma_f32 v40, v46, v40, v56
	v_fma_f32 v41, v47, v41, v57
	v_fma_f32 v38, v48, v38, v54
	v_fma_f32 v39, v49, v39, v55
	v_bfe_u32 v48, v40, 16, 1
	v_bfe_u32 v46, v38, 16, 1
	v_bfe_u32 v47, v39, 16, 1
	v_bfe_u32 v49, v41, 16, 1
	v_add3_u32 v38, v38, v46, s34
	v_add3_u32 v40, v40, v48, s34
	v_add3_u32 v39, v39, v47, s34
	v_add3_u32 v41, v41, v49, s34
	v_lshrrev_b32_e32 v38, 16, v38
	v_lshrrev_b32_e32 v40, 16, v40
	v_and_or_b32 v38, v39, s35, v38
	v_and_or_b32 v39, v41, s35, v40
	global_store_dwordx2 v[68:69], v[38:39], off offset:1024
	global_load_dwordx4 v[38:41], v[62:63], off offset:3072
	s_nop 0
	global_load_dwordx4 v[46:49], v80, s[70:71]
	global_load_dwordx4 v[50:53], v77, s[64:65] offset:3072
	s_waitcnt vmcnt(2)
	v_mul_f32_e32 v38, v38, v42
	v_mul_f32_e32 v39, v39, v43
	v_mul_f32_e32 v40, v40, v44
	v_mul_f32_e32 v41, v41, v45
	s_waitcnt vmcnt(1)
	v_add_f32_e32 v42, 1.0, v48
	v_add_f32_e32 v43, 1.0, v49
	v_add_f32_e32 v44, 1.0, v46
	v_add_f32_e32 v45, 1.0, v47
	s_waitcnt vmcnt(0)
	v_fma_f32 v40, v42, v40, v52
	v_fma_f32 v41, v43, v41, v53
	v_fma_f32 v38, v44, v38, v50
	v_fma_f32 v39, v45, v39, v51
	v_bfe_u32 v44, v40, 16, 1
	v_bfe_u32 v42, v38, 16, 1
	v_bfe_u32 v43, v39, 16, 1
	v_bfe_u32 v45, v41, 16, 1
	v_add3_u32 v38, v38, v42, s34
	v_add3_u32 v40, v40, v44, s34
	v_add3_u32 v39, v39, v43, s34
	v_add3_u32 v41, v41, v45, s34
	v_lshrrev_b32_e32 v38, 16, v38
	v_lshrrev_b32_e32 v40, 16, v40
	v_and_or_b32 v38, v39, s35, v38
	v_and_or_b32 v39, v41, s35, v40
	global_store_dwordx2 v[68:69], v[38:39], off offset:1536
	s_andn2_b64 vcc, exec, s[46:47]
	s_cbranch_vccz .LBB0_136

; __device__ __forceinline__ unsigned pk2(float lo, float hi) { return f2bf(lo) | (f2bf(hi) << 16); }
; __global__ void __launch_bounds__(NTHR, 2) mega(Args args) {
;     ...
; #pragma unroll
;             for (int q = 0; q < 4; ++q) {
;                 if (!ok[q]) continue;
;                 const int m = mrow_[q]; const int b = m / LT, w = m % LT;
;                 const float* mrow = mod + (size_t)(w < CT ? 8 : b) * NMODC;
;                 const float rstd = rsqrtf(ss[q] * (1.f / D) + EPS);
; #pragma unroll
;                 for (int j2 = 0; j2 < 4; ++j2) { const int k0 = 4 * lane + 256 * j2;
;                     const f32x4 g = *(const f32x4*)(g1 + k0), sc = *(const f32x4*)(mrow + D + k0), sh = *(const f32x4*)(mrow + k0);
;                     const f32x4 y = v[q][j2] * rstd * g; const f32x4 h = y * (sc + 1.f) + sh;
;                     v2u pk; pk.x = pk2(h.x, h.y); pk.y = pk2(h.z, h.w);
;                     *(v2u*)(HB + (size_t)m * D + k0) = pk; }
.LBB0_136:
	s_and_b64 s[42:43], s[48:49], exec
	s_cselect_b32 s5, 8, s38
	s_mul_hi_i32 s7, s5, 0x6000
	s_mulk_i32 s5, 0x6000
	s_add_u32 s38, s28, s5
	s_addc_u32 s39, s29, s7
	s_add_u32 s46, s38, 0x1000
	global_load_dwordx4 v[38:41], v[62:63], off
	s_addc_u32 s47, s39, 0
	global_load_dwordx4 v[42:45], v77, s[46:47]
	global_load_dwordx4 v[46:49], v77, s[38:39]
	s_waitcnt lgkmcnt(1)
	v_add_f32_e32 v28, v28, v29
	v_fmamk_f32 v28, v28, 0x3a800000, v76
	v_mul_f32_e32 v29, 0x4b800000, v28
	v_cmp_gt_f32_e32 vcc, s19, v28
	s_ashr_i32 s21, s20, 31
	s_lshl_b64 s[20:21], s[20:21], 11
	v_cndmask_b32_e32 v28, v28, v29, vcc
	v_rsq_f32_e32 v28, v28
	v_lshl_add_u64 v[50:51], v[64:65], 0, s[20:21]
	v_mul_f32_e32 v29, 0x45800000, v28
	v_cndmask_b32_e32 v52, v28, v29, vcc
	v_mul_f32_e32 v28, v52, v36
	v_mul_f32_e32 v29, v52, v37
	v_mul_f32_e32 v34, v52, v34
	v_mul_f32_e32 v35, v52, v35
	v_mul_f32_e32 v30, v52, v30
	v_mul_f32_e32 v31, v52, v31
	v_mul_f32_e32 v24, v52, v24
	v_mul_f32_e32 v25, v52, v25
	v_mul_f32_e32 v22, v52, v22
	v_mul_f32_e32 v23, v52, v23
	v_mul_f32_e32 v20, v52, v20
	v_mul_f32_e32 v21, v52, v21
	v_mul_f32_e32 v18, v52, v18
	v_mul_f32_e32 v19, v52, v19
	s_waitcnt vmcnt(2)
	v_mul_f32_e32 v34, v38, v34
	v_mul_f32_e32 v35, v39, v35
	v_mul_f32_e32 v28, v40, v28
	v_mul_f32_e32 v29, v41, v29
	s_waitcnt vmcnt(1)
	v_add_f32_e32 v36, 1.0, v44
	v_add_f32_e32 v37, 1.0, v45
	v_add_f32_e32 v38, 1.0, v42
	v_add_f32_e32 v39, 1.0, v43
	s_waitcnt vmcnt(0)
	v_fma_f32 v28, v36, v28, v48
	v_fma_f32 v29, v37, v29, v49
	v_fma_f32 v34, v38, v34, v46
	v_fma_f32 v35, v39, v35, v47
	v_bfe_u32 v38, v28, 16, 1
	v_bfe_u32 v36, v34, 16, 1
	v_bfe_u32 v37, v35, 16, 1
	v_bfe_u32 v39, v29, 16, 1
	v_add3_u32 v34, v34, v36, s34
	v_add3_u32 v28, v28, v38, s34
	v_add3_u32 v35, v35, v37, s34
	v_add3_u32 v29, v29, v39, s34
	v_lshrrev_b32_e32 v34, 16, v34
	v_lshrrev_b32_e32 v36, 16, v28
	v_and_or_b32 v28, v35, s35, v34
	v_and_or_b32 v29, v29, s35, v36
	global_store_dwordx2 v[50:51], v[28:29], off
	global_load_dwordx4 v[34:37], v[62:63], off offset:1024
	global_load_dwordx4 v[38:41], v78, s[46:47]
	global_load_dwordx4 v[42:45], v77, s[38:39] offset:1024
	v_mul_f32_e32 v28, v52, v32
	v_mul_f32_e32 v29, v52, v33
	s_waitcnt vmcnt(2)
	v_mul_f32_e32 v30, v34, v30
	v_mul_f32_e32 v31, v35, v31
	v_mul_f32_e32 v28, v36, v28
	v_mul_f32_e32 v29, v37, v29
	s_waitcnt vmcnt(1)
	v_add_f32_e32 v32, 1.0, v40
	v_add_f32_e32 v33, 1.0, v41
	v_add_f32_e32 v34, 1.0, v38
	v_add_f32_e32 v35, 1.0, v39
	s_waitcnt vmcnt(0)
	v_fma_f32 v28, v32, v28, v44
	v_fma_f32 v29, v33, v29, v45
	v_fma_f32 v30, v34, v30, v42
	v_fma_f32 v31, v35, v31, v43
	v_bfe_u32 v34, v28, 16, 1
	v_bfe_u32 v32, v30, 16, 1
	v_bfe_u32 v33, v31, 16, 1
	v_bfe_u32 v35, v29, 16, 1
	v_add3_u32 v30, v30, v32, s34
	v_add3_u32 v28, v28, v34, s34
	v_add3_u32 v31, v31, v33, s34
	v_add3_u32 v29, v29, v35, s34
	v_lshrrev_b32_e32 v30, 16, v30
	v_lshrrev_b32_e32 v32, 16, v28
	v_and_or_b32 v28, v31, s35, v30
	v_and_or_b32 v29, v29, s35, v32
	global_store_dwordx2 v[50:51], v[28:29], off offset:512
	global_load_dwordx4 v[28:31], v[62:63], off offset:2048
	s_nop 0
	global_load_dwordx4 v[32:35], v79, s[46:47]
	global_load_dwordx4 v[36:39], v77, s[38:39] offset:2048
	s_waitcnt vmcnt(2)
	v_mul_f32_e32 v22, v28, v22
	v_mul_f32_e32 v23, v29, v23
	v_mul_f32_e32 v24, v30, v24
	v_mul_f32_e32 v25, v31, v25
	s_waitcnt vmcnt(1)
	v_add_f32_e32 v28, 1.0, v34
	v_add_f32_e32 v29, 1.0, v35
	v_add_f32_e32 v30, 1.0, v32
	v_add_f32_e32 v31, 1.0, v33
	s_waitcnt vmcnt(0)
	v_fma_f32 v24, v28, v24, v38
	v_fma_f32 v25, v29, v25, v39
	v_fma_f32 v22, v30, v22, v36
	v_fma_f32 v23, v31, v23, v37
	v_bfe_u32 v30, v24, 16, 1
	v_bfe_u32 v28, v22, 16, 1
	v_bfe_u32 v29, v23, 16, 1
	v_bfe_u32 v31, v25, 16, 1
	v_add3_u32 v22, v22, v28, s34
	v_add3_u32 v24, v24, v30, s34
	v_add3_u32 v23, v23, v29, s34
	v_add3_u32 v25, v25, v31, s34
	v_lshrrev_b32_e32 v22, 16, v22
	v_lshrrev_b32_e32 v24, 16, v24
	v_and_or_b32 v22, v23, s35, v22
	v_and_or_b32 v23, v25, s35, v24
	global_store_dwordx2 v[50:51], v[22:23], off offset:1024
	global_load_dwordx4 v[22:25], v[62:63], off offset:3072
	s_nop 0
	global_load_dwordx4 v[28:31], v80, s[46:47]
	global_load_dwordx4 v[32:35], v77, s[38:39] offset:3072
	s_waitcnt vmcnt(2)
	v_mul_f32_e32 v18, v22, v18
	v_mul_f32_e32 v19, v23, v19
	v_mul_f32_e32 v20, v24, v20
	v_mul_f32_e32 v21, v25, v21
	s_waitcnt vmcnt(1)
	v_add_f32_e32 v22, 1.0, v30
	v_add_f32_e32 v23, 1.0, v31
	v_add_f32_e32 v24, 1.0, v28
	v_add_f32_e32 v25, 1.0, v29
	s_waitcnt vmcnt(0)
	v_fma_f32 v20, v22, v20, v34
	v_fma_f32 v21, v23, v21, v35
	v_fma_f32 v18, v24, v18, v32
	v_fma_f32 v19, v25, v19, v33
	v_bfe_u32 v24, v20, 16, 1
	v_bfe_u32 v22, v18, 16, 1
	v_bfe_u32 v23, v19, 16, 1
	v_bfe_u32 v25, v21, 16, 1
	v_add3_u32 v18, v18, v22, s34
	v_add3_u32 v20, v20, v24, s34
	v_add3_u32 v19, v19, v23, s34
	v_add3_u32 v21, v21, v25, s34
	v_lshrrev_b32_e32 v18, 16, v18
	v_lshrrev_b32_e32 v20, 16, v20
	v_and_or_b32 v18, v19, s35, v18
	v_and_or_b32 v19, v21, s35, v20
	global_store_dwordx2 v[50:51], v[18:19], off offset:1536
	s_andn2_b64 vcc, exec, s[14:15]
	s_cbranch_vccnz .LBB0_131
; __device__ __forceinline__ unsigned pk2(float lo, float hi) { return f2bf(lo) | (f2bf(hi) << 16); }
; __global__ void __launch_bounds__(NTHR, 2) mega(Args args) {
;     ...
; #pragma unroll
;             for (int q = 0; q < 4; ++q) {
;                 if (!ok[q]) continue;
;                 const int m = mrow_[q]; const int b = m / LT, w = m % LT;
;                 const float* mrow = mod + (size_t)(w < CT ? 8 : b) * NMODC;
;                 const float rstd = rsqrtf(ss[q] * (1.f / D) + EPS);
; #pragma unroll
;                 for (int j2 = 0; j2 < 4; ++j2) { const int k0 = 4 * lane + 256 * j2;
;                     const f32x4 g = *(const f32x4*)(g1 + k0), sc = *(const f32x4*)(mrow + D + k0), sh = *(const f32x4*)(mrow + k0);
;                     const f32x4 y = v[q][j2] * rstd * g; const f32x4 h = y * (sc + 1.f) + sh;
;                     v2u pk; pk.x = pk2(h.x, h.y); pk.y = pk2(h.z, h.w);
;                     *(v2u*)(HB + (size_t)m * D + k0) = pk; }
.LBB0_137:
	s_and_b64 s[14:15], s[16:17], exec
	s_cselect_b32 s5, 8, s8
	s_mul_hi_i32 s7, s5, 0x6000
	s_mulk_i32 s5, 0x6000
	s_add_u32 s8, s28, s5
	s_addc_u32 s9, s29, s7
	s_add_u32 s14, s8, 0x1000
	global_load_dwordx4 v[18:21], v[62:63], off
	s_addc_u32 s15, s9, 0
	global_load_dwordx4 v[22:25], v77, s[14:15]
	s_waitcnt lgkmcnt(1)
	global_load_dwordx4 v[28:31], v77, s[8:9]
	s_waitcnt lgkmcnt(0)
	v_add_f32_e32 v26, v26, v27
	v_fmamk_f32 v26, v26, 0x3a800000, v76
	v_mul_f32_e32 v27, 0x4b800000, v26
	v_cmp_gt_f32_e32 vcc, s19, v26
	s_ashr_i32 s7, s6, 31
	s_lshl_b64 s[6:7], s[6:7], 11
	v_cndmask_b32_e32 v26, v26, v27, vcc
	v_rsq_f32_e32 v32, v26
	v_lshl_add_u64 v[26:27], v[64:65], 0, s[6:7]
	v_mul_f32_e32 v33, 0x45800000, v32
	v_cndmask_b32_e32 v32, v32, v33, vcc
	v_mul_f32_e32 v16, v32, v16
	v_mul_f32_e32 v17, v32, v17
	v_mul_f32_e32 v14, v32, v14
	v_mul_f32_e32 v15, v32, v15
	v_mul_f32_e32 v12, v32, v12
	v_mul_f32_e32 v13, v32, v13
	v_mul_f32_e32 v10, v32, v10
	v_mul_f32_e32 v11, v32, v11
	v_mul_f32_e32 v8, v32, v8
	v_mul_f32_e32 v9, v32, v9
	v_mul_f32_e32 v6, v32, v6
	v_mul_f32_e32 v7, v32, v7
	v_mul_f32_e32 v4, v32, v4
	v_mul_f32_e32 v5, v32, v5
	v_mul_f32_e32 v2, v32, v2
	v_mul_f32_e32 v3, v32, v3
	s_waitcnt vmcnt(2)
	v_mul_f32_e32 v14, v18, v14
	v_mul_f32_e32 v15, v19, v15
	v_mul_f32_e32 v16, v20, v16
	v_mul_f32_e32 v17, v21, v17
	s_waitcnt vmcnt(1)
	v_add_f32_e32 v18, 1.0, v24
	v_add_f32_e32 v19, 1.0, v25
	v_add_f32_e32 v20, 1.0, v22
	v_add_f32_e32 v21, 1.0, v23
	s_waitcnt vmcnt(0)
	v_fma_f32 v16, v18, v16, v30
	v_fma_f32 v17, v19, v17, v31
	v_fma_f32 v14, v20, v14, v28
	v_fma_f32 v15, v21, v15, v29
	v_bfe_u32 v20, v16, 16, 1
	v_bfe_u32 v18, v14, 16, 1
	v_bfe_u32 v19, v15, 16, 1
	v_bfe_u32 v21, v17, 16, 1
	v_add3_u32 v14, v14, v18, s34
	v_add3_u32 v16, v16, v20, s34
	v_add3_u32 v15, v15, v19, s34
	v_add3_u32 v17, v17, v21, s34
	v_lshrrev_b32_e32 v14, 16, v14
	v_lshrrev_b32_e32 v16, 16, v16
	v_and_or_b32 v14, v15, s35, v14
	v_and_or_b32 v15, v17, s35, v16
	global_store_dwordx2 v[26:27], v[14:15], off
	global_load_dwordx4 v[14:17], v[62:63], off offset:1024
	s_nop 0
	global_load_dwordx4 v[18:21], v78, s[14:15]
	global_load_dwordx4 v[22:25], v77, s[8:9] offset:1024
	s_waitcnt vmcnt(2)
	v_mul_f32_e32 v10, v14, v10
	v_mul_f32_e32 v11, v15, v11
	v_mul_f32_e32 v12, v16, v12
	v_mul_f32_e32 v13, v17, v13
	s_waitcnt vmcnt(1)
	v_add_f32_e32 v14, 1.0, v20
	v_add_f32_e32 v15, 1.0, v21
	v_add_f32_e32 v16, 1.0, v18
	v_add_f32_e32 v17, 1.0, v19
	s_waitcnt vmcnt(0)
	v_fma_f32 v12, v14, v12, v24
	v_fma_f32 v13, v15, v13, v25
	v_fma_f32 v10, v16, v10, v22
	v_fma_f32 v11, v17, v11, v23
	v_bfe_u32 v16, v12, 16, 1
	v_bfe_u32 v14, v10, 16, 1
	v_bfe_u32 v15, v11, 16, 1
	v_bfe_u32 v17, v13, 16, 1
	v_add3_u32 v10, v10, v14, s34
	v_add3_u32 v12, v12, v16, s34
	v_add3_u32 v11, v11, v15, s34
	v_add3_u32 v13, v13, v17, s34
	v_lshrrev_b32_e32 v10, 16, v10
	v_lshrrev_b32_e32 v12, 16, v12
	v_and_or_b32 v10, v11, s35, v10
	v_and_or_b32 v11, v13, s35, v12
	global_store_dwordx2 v[26:27], v[10:11], off offset:512
	global_load_dwordx4 v[10:13], v[62:63], off offset:2048
	s_nop 0
	global_load_dwordx4 v[14:17], v79, s[14:15]
	global_load_dwordx4 v[18:21], v77, s[8:9] offset:2048
	s_waitcnt vmcnt(2)
	v_mul_f32_e32 v6, v10, v6
	v_mul_f32_e32 v7, v11, v7
	v_mul_f32_e32 v8, v12, v8
	v_mul_f32_e32 v9, v13, v9
	s_waitcnt vmcnt(1)
	v_add_f32_e32 v10, 1.0, v16
	v_add_f32_e32 v11, 1.0, v17
	v_add_f32_e32 v12, 1.0, v14
	v_add_f32_e32 v13, 1.0, v15
	s_waitcnt vmcnt(0)
	v_fma_f32 v8, v10, v8, v20
	v_fma_f32 v9, v11, v9, v21
	v_fma_f32 v6, v12, v6, v18
	v_fma_f32 v7, v13, v7, v19
	v_bfe_u32 v12, v8, 16, 1
	v_bfe_u32 v10, v6, 16, 1
	v_bfe_u32 v11, v7, 16, 1
	v_bfe_u32 v13, v9, 16, 1
	v_add3_u32 v6, v6, v10, s34
	v_add3_u32 v8, v8, v12, s34
	v_add3_u32 v7, v7, v11, s34
	v_add3_u32 v9, v9, v13, s34
	v_lshrrev_b32_e32 v6, 16, v6
	v_lshrrev_b32_e32 v8, 16, v8
	v_and_or_b32 v6, v7, s35, v6
	v_and_or_b32 v7, v9, s35, v8
	global_store_dwordx2 v[26:27], v[6:7], off offset:1024
	global_load_dwordx4 v[6:9], v[62:63], off offset:3072
	s_nop 0
	global_load_dwordx4 v[10:13], v80, s[14:15]
	global_load_dwordx4 v[14:17], v77, s[8:9] offset:3072
	s_waitcnt vmcnt(2)
	v_mul_f32_e32 v2, v6, v2
	v_mul_f32_e32 v3, v7, v3
	v_mul_f32_e32 v4, v8, v4
	v_mul_f32_e32 v5, v9, v5
	s_waitcnt vmcnt(1)
	v_add_f32_e32 v6, 1.0, v12
	v_add_f32_e32 v7, 1.0, v13
	v_add_f32_e32 v8, 1.0, v10
	v_add_f32_e32 v9, 1.0, v11
	s_waitcnt vmcnt(0)
	v_fma_f32 v4, v6, v4, v16
	v_fma_f32 v5, v7, v5, v17
	v_fma_f32 v2, v8, v2, v14
	v_fma_f32 v3, v9, v3, v15
	v_bfe_u32 v8, v4, 16, 1
	v_bfe_u32 v6, v2, 16, 1
	v_bfe_u32 v7, v3, 16, 1
	v_bfe_u32 v9, v5, 16, 1
	v_add3_u32 v2, v2, v6, s34
	v_add3_u32 v4, v4, v8, s34
	v_add3_u32 v3, v3, v7, s34
	v_add3_u32 v5, v5, v9, s34
	v_lshrrev_b32_e32 v2, 16, v2
	v_lshrrev_b32_e32 v4, 16, v4
	v_and_or_b32 v2, v3, s35, v2
	v_and_or_b32 v3, v5, s35, v4
	global_store_dwordx2 v[26:27], v[2:3], off offset:1536
	s_branch .LBB0_131
